# v41 with K-loop setprio flips removed and one static setprio 1 for waves 4-7
# speedup vs baseline: 1.0064x; 1.0055x over previous
; __device__ __forceinline__ int tidx() { int t = threadIdx.x; asm volatile("" : "+v"(t)); return t; }
; #define PG8_STAGE(bufoff, gbase, voff) do { _Pragma("unroll") for (int _i = 0; _i < 2; ++_i) \
;         __builtin_amdgcn_global_load_lds((const unsigned*)((const char*)(gbase) + (voff)[_i]), (LAS unsigned*)(lds + (bufoff) + ldsw + _i * 8192), 16, 0, 0); } while (0)
; #define PG8_WAIT_V(n) asm volatile("s_waitcnt vmcnt(" #n ")" ::: "memory")
; #define PG8_BAR __builtin_amdgcn_s_barrier()
; template <class Epi>
; __device__ __forceinline__ void gemm_phase(LAS unsigned char* lds, const Gemm g, const StaticOrder& S, const Epi& E) {
;     const int tid = tidx(), wid = __builtin_amdgcn_readfirstlane(tid >> 6), lane = tid & 63, wr = wid >> 2, wc = wid & 3, fr = lane & 15, fq = lane >> 4;
;     const int K = g.K, nt = K / BK;
;     unsigned voffA[2], voffB[2];
; #pragma unroll
;     for (int i = 0; i < 2; ++i) { int R, C; stage_rc(tid * 16 + i * 8192, R, C); const int Rb = E.PERM ? ((R & ~31) + perm32(R & 31)) : R;
;         voffA[i] = (unsigned)(R * K + C) * 2u; voffB[i] = (unsigned)(Rb * K + C) * 2u; }
;     const size_t kstep = (size_t)(BK * 2);
;     const size_t hstep = (size_t)HALF * K * 2;
;     const size_t tstep = 2 * hstep;
;     const unsigned ldsw = (unsigned)wid * 1024u;
;     const int aoff = lds_byte(wr * 64 + fr, fq * 8), boff = lds_byte(wc * 32 + fr, fq * 8);
;     ...
;     Unit cur, nxt; int ui = 0;
;     if (!S.next(0, cur)) return;
;     f32x4 acc[2][2][4][2];
; #pragma unroll
;     for (int a = 0; a < 2; ++a)
; #pragma unroll
;         for (int b = 0; b < 2; ++b)
; #pragma unroll
;             for (int m = 0; m < 4; ++m)
; #pragma unroll
;                 for (int n = 0; n < 2; ++n) acc[a][b][m][n] = (f32x4){0.f, 0.f, 0.f, 0.f};
;     bf16x8 At[4][2], B0[2][2], B1[2][2];
;     const char* cA = (const char*)g.A + (size_t)cur.pm * tstep; const char* cB = (const char*)g.Bt + (size_t)cur.pn * tstep;
;     PG8_STAGE(PG8_SB(0, 0), cB, voffB); PG8_STAGE(PG8_SA(0, 0), cA, voffA); PG8_STAGE(PG8_SB(0, 1), cB + hstep, voffB); PG8_STAGE(PG8_SA(0, 1), cA + hstep, voffA);
;     if (wr == 1) PG8_BAR;
;     PG8_WAIT_V(4); PG8_BAR;
;     PG8_STAGE(PG8_SB(1, 0), cB + kstep, voffB); PG8_STAGE(PG8_SA(1, 0), cA + kstep, voffA); PG8_STAGE(PG8_SB(1, 1), cB + hstep + kstep, voffB);
;     PG8_WAIT_V(6); PG8_BAR;
.LBB0_191:
	s_andn2_b64 vcc, exec, s[36:37]
	s_cbranch_vccnz .LBB0_285
	v_bfe_i32 v4, v0, 27, 1
	v_lshlrev_b32_e32 v2, 4, v0
	v_lshrrev_b32_e32 v4, 22, v4
	v_add_u32_e32 v4, v2, v4
	v_and_b32_e32 v4, 0xfffffc00, v4
	v_sub_u32_e32 v4, v2, v4
	v_lshrrev_b32_e32 v5, 4, v4
	v_ashrrev_i32_e32 v3, 31, v0
	v_bitop3_b32 v5, v5, v4, 32 bitop3:0x6c
	v_ashrrev_i32_e32 v4, 31, v4
	v_lshrrev_b32_e32 v3, 26, v3
	v_lshrrev_b32_e32 v4, 26, v4
	v_add_u32_e32 v3, v0, v3
	v_add_u32_e32 v4, v5, v4
	v_ashrrev_i32_e32 v3, 6, v3
	v_ashrrev_i32_e32 v4, 6, v4
	v_lshlrev_b32_e32 v6, 3, v3
	v_mul_i32_i24_e32 v7, 64, v4
	v_and_b32_e32 v6, -16, v6
	v_lshlrev_b32_e32 v3, 5, v3
	v_sub_u32_e32 v5, v5, v7
	v_add_u32_e32 v6, v4, v6
	v_and_b32_e32 v3, 32, v3
	v_ashrrev_i16_sdwa v5, v210, sext(v5) dst_sel:DWORD dst_unused:UNUSED_PAD src0_sel:DWORD src1_sel:BYTE_0
	v_add_u32_sdwa v3, v3, sext(v5) dst_sel:DWORD dst_unused:UNUSED_PAD src0_sel:DWORD src1_sel:WORD_0
	v_lshlrev_b32_e32 v5, 1, v6
	v_lshrrev_b32_e32 v7, 2, v6
	v_and_b32_e32 v4, 3, v4
	s_movk_i32 s4, 0xffe0
	v_and_b32_e32 v5, 24, v5
	v_and_b32_e32 v7, 4, v7
	v_and_or_b32 v4, v6, s4, v4
	v_or3_b32 v4, v4, v7, v5
	v_mul_lo_u32 v5, v6, s3
	v_mul_lo_u32 v4, v4, s3
	v_add_u32_e32 v2, 0x2000, v2
	v_add_lshl_u32 v168, v3, v5, 1
	v_add_lshl_u32 v170, v4, v3, 1
	v_ashrrev_i32_e32 v3, 31, v2
	v_lshrrev_b32_e32 v3, 22, v3
	v_add_u32_e32 v3, v2, v3
	v_ashrrev_i32_e32 v3, 10, v3
	v_mul_i32_i24_e32 v4, 0x400, v3
	v_sub_u32_e32 v2, v2, v4
	v_lshrrev_b32_e32 v4, 4, v2
	v_bitop3_b32 v2, v4, v2, 32 bitop3:0x6c
	v_ashrrev_i32_e32 v5, 31, v2
	v_writelane_b32 v245, s56, 47
	v_lshrrev_b32_e32 v5, 26, v5
	v_lshlrev_b32_e32 v4, 3, v3
	v_writelane_b32 v245, s57, 48
	v_add_u32_e32 v5, v2, v5
	v_writelane_b32 v245, s18, 45
	v_and_b32_e32 v4, -16, v4
	v_ashrrev_i32_e32 v6, 6, v5
	v_writelane_b32 v245, s19, 46
	v_add_u32_e32 v4, v6, v4
	v_and_b32_e32 v5, 0xc0, v5
	v_and_b32_e32 v6, 3, v6
	s_lshl_b32 s18, s3, 9
	s_ashr_i32 s5, s97, 31
	s_ashr_i32 s8, s0, 31
	s_ashr_i32 s1, s10, 6
	v_lshlrev_b32_e32 v3, 5, v3
	v_sub_u32_e32 v2, v2, v5
	v_and_or_b32 v6, v4, s4, v6
	v_writelane_b32 v245, s10, 51
	s_ashr_i32 s4, s10, 8
	s_mul_i32 s5, s18, s5
	s_mul_hi_u32 s7, s18, s97
	s_mul_i32 s8, s18, s8
	s_mul_hi_u32 s10, s18, s0
	v_and_b32_e32 v3, 32, v3
	v_ashrrev_i16_sdwa v2, v210, sext(v2) dst_sel:DWORD dst_unused:UNUSED_PAD src0_sel:DWORD src1_sel:BYTE_0
	s_lshl_b32 s13, s3, 8
	s_lshl_b32 s6, s1, 10
	s_add_i32 s7, s7, s5
	s_add_i32 s10, s10, s8
	s_mul_i32 s8, s18, s0
	v_add_u32_sdwa v2, v3, sext(v2) dst_sel:DWORD dst_unused:UNUSED_PAD src0_sel:DWORD src1_sel:WORD_0
	v_lshlrev_b32_e32 v3, 1, v4
	v_lshrrev_b32_e32 v5, 2, v4
	s_add_u32 s54, s44, s8
	v_and_b32_e32 v3, 24, v3
	v_and_b32_e32 v5, 4, v5
	s_addc_u32 s55, s45, s10
	s_add_i32 s11, s6, 0
	v_or3_b32 v3, v6, v5, v3
	s_add_i32 m0, s11, 0x10000
	v_mul_lo_u32 v3, v3, s3
	s_mul_i32 s5, s18, s97
	global_load_lds_dwordx4 v170, s[54:55]
	s_add_i32 m0, s11, 0x12000
	v_add_lshl_u32 v174, v3, v2, 1
	s_add_u32 s64, s48, s5
	v_mul_lo_u32 v4, v4, s3
	global_load_lds_dwordx4 v174, s[54:55]
	s_addc_u32 s65, s49, s7
	s_mov_b32 m0, s11
	s_add_i32 s70, s11, 0x2000
	v_add_lshl_u32 v172, v2, v4, 1
	global_load_lds_dwordx4 v168, s[64:65]
	s_mov_b32 m0, s70
	s_add_u32 s30, s54, s13
	global_load_lds_dwordx4 v172, s[64:65]
	s_addc_u32 s31, s55, 0
	s_add_i32 m0, s11, 0x14000
	v_mov_b32_e32 v171, v1
	global_load_lds_dwordx4 v170, s[30:31]
	s_add_i32 m0, s11, 0x16000
	s_add_u32 s36, s64, s13
	s_addc_u32 s37, s65, 0
	s_add_i32 s71, s11, 0x4000
	global_load_lds_dwordx4 v174, s[30:31]
	s_mov_b32 m0, s71
	s_add_i32 s19, s11, 0x6000
	global_load_lds_dwordx4 v168, s[36:37]
	s_mov_b32 m0, s19
	v_mov_b32_e32 v175, v1
	global_load_lds_dwordx4 v172, s[36:37]
	v_mov_b32_e32 v169, v1
	v_mov_b32_e32 v173, v1
	v_readlane_b32 s80, v245, 55
	s_waitcnt vmcnt(0)
	v_lshl_add_u64 v[12:13], s[54:55], 0, v[170:171]
	v_lshl_add_u64 v[10:11], s[54:55], 0, v[174:175]
	v_lshl_add_u64 v[8:9], s[64:65], 0, v[168:169]
	v_lshl_add_u64 v[6:7], s[64:65], 0, v[172:173]
	v_lshl_add_u64 v[4:5], s[30:31], 0, v[170:171]
	s_cmp_lg_u32 s4, 1
	v_lshl_add_u64 v[2:3], s[30:31], 0, v[174:175]
	v_readlane_b32 s81, v245, 56
	s_cbranch_scc1 .LBB0_194
	s_setprio 1
	s_barrier

; #define PG8_STAGE(bufoff, gbase, voff) do { _Pragma("unroll") for (int _i = 0; _i < 2; ++_i) \
;         __builtin_amdgcn_global_load_lds((const unsigned*)((const char*)(gbase) + (voff)[_i]), (LAS unsigned*)(lds + (bufoff) + ldsw + _i * 8192), 16, 0, 0); } while (0)
; #define PG8_LDA(dst, b, h) do { _Pragma("unroll") for (int m = 0; m < 4; ++m) _Pragma("unroll") for (int k = 0; k < 2; ++k) dst[m][k] = *(const LAS bf16x8*)(lds + PG8_SA(b, h) + aoff + m * 2048 + k * 1024); } while (0)
; #define PG8_LDB(dst, b, h) do { _Pragma("unroll") for (int n = 0; n < 2; ++n) _Pragma("unroll") for (int k = 0; k < 2; ++k) dst[n][k] = *(const LAS bf16x8*)(lds + PG8_SB(b, h) + boff + n * 2048 + k * 1024); } while (0)
; #define PG8_MMA(ai, bj, At, Bt) do { __builtin_amdgcn_s_setprio(1); _Pragma("unroll") for (int m = 0; m < 4; ++m) _Pragma("unroll") for (int n = 0; n < 2; ++n) _Pragma("unroll") for (int k = 0; k < 2; ++k) \
;         acc[ai][bj][m][n] = __builtin_amdgcn_mfma_f32_16x16x32_bf16(Bt[n][k], At[m][k], acc[ai][bj][m][n], 0, 0, 0); __builtin_amdgcn_s_setprio(0); } while (0)
; #define PG8_WAIT_V(n) asm volatile("s_waitcnt vmcnt(" #n ")" ::: "memory")
; #define PG8_WAIT_L(n) asm volatile("s_waitcnt lgkmcnt(" #n ")" ::: "memory")
; #define PG8_BAR __builtin_amdgcn_s_barrier()
; template <class Epi>
; __device__ __forceinline__ void gemm_phase(LAS unsigned char* lds, const Gemm g, const StaticOrder& S, const Epi& E) {
;     ...
;         for (; t < tend; t += 2) {
;             const bool last = (t == nt - 2);
;             const char* a1 = cA + (size_t)(t + 1) * kstep;
;             const char* a2 = last ? nA : cA + (size_t)(t + 2) * kstep; const char* b2 = last ? nB : cB + (size_t)(t + 2) * kstep;
;             const char* a3 = a2 + kstep; const char* b3 = b2 + kstep;
;             PG8_LDB(B0, 0, 0); PG8_SCHED; PG8_LDA(At, 0, 0); PG8_STAGE(PG8_SA(1, 1), a1 + hstep, voffA);
;             PG8_WAIT_L(8); PG8_BAR; PG8_WAIT_L(0); PG8_MMA(0, 0, At, B0); PG8_BAR; PG8_SCHED;
;             PG8_LDB(B1, 0, 1); PG8_STAGE(PG8_SB(0, 0), b2, voffB);
;             PG8_BAR; PG8_WAIT_L(0); PG8_MMA(0, 1, At, B1); PG8_BAR;
;             PG8_LDA(At, 0, 1); PG8_STAGE(PG8_SA(0, 0), a2, voffA);
;             PG8_BAR; PG8_WAIT_L(0); PG8_MMA(1, 0, At, B0); PG8_BAR; PG8_SCHED;
;             PG8_STAGE(PG8_SB(0, 1), b2 + hstep, voffB);
;             PG8_WAIT_V(6); PG8_BAR; PG8_MMA(1, 1, At, B1); PG8_BAR;
.LBB0_206:
	s_add_i32 s78, 0, 0x10000
	v_add_u32_e32 v3, s78, v195
	ds_read_b128 v[132:135], v3
	ds_read_b128 v[136:139], v3 offset:1024
	ds_read_b128 v[140:143], v3 offset:2048
	ds_read_b128 v[144:147], v3 offset:3072
	s_add_i32 s76, s2, 1
	s_mov_b32 s47, s2
	s_add_i32 s2, s2, 2
	s_ashr_i32 s77, s76, 31
	s_cmp_eq_u32 s67, s47
	s_cselect_b32 s75, s43, s46
	s_cselect_b32 s74, s42, vcc_hi
	s_cselect_b32 s93, s63, vcc_lo
	s_cselect_b32 s92, s62, s3
	s_lshl_b64 s[76:77], s[76:77], 7
	s_add_u32 s76, s5, s76
	s_addc_u32 s77, s31, s77
	v_lshl_add_u64 v[182:183], s[76:77], 0, v[168:169]
	s_add_i32 m0, s11, 0xc000
	ds_read_b128 v[148:151], v200
	ds_read_b128 v[152:155], v200 offset:1024
	ds_read_b128 v[156:159], v200 offset:2048
	ds_read_b128 v[160:163], v200 offset:3072
	ds_read_b128 v[164:167], v200 offset:4096
	ds_read_b128 v[186:189], v200 offset:5120
	ds_read_b128 v[190:193], v200 offset:6144
	ds_read_b128 v[202:205], v200 offset:7168
	global_load_lds_dwordx4 v[182:183], off
	v_lshl_add_u64 v[182:183], s[76:77], 0, v[172:173]
	s_add_i32 m0, s11, 0xe000
	s_nop 0
	global_load_lds_dwordx4 v[182:183], off
	s_waitcnt lgkmcnt(0)
	s_barrier
	v_mfma_f32_16x16x32_bf16 v[128:131], v[132:135], v[148:151], v[128:131]
	v_mfma_f32_16x16x32_bf16 v[124:127], v[140:143], v[148:151], v[124:127]
	v_mfma_f32_16x16x32_bf16 v[112:115], v[132:135], v[156:159], v[112:115]
	v_mfma_f32_16x16x32_bf16 v[108:111], v[140:143], v[156:159], v[108:111]
	v_mfma_f32_16x16x32_bf16 v[96:99], v[132:135], v[164:167], v[96:99]
	v_mfma_f32_16x16x32_bf16 v[92:95], v[140:143], v[164:167], v[92:95]
	v_mfma_f32_16x16x32_bf16 v[80:83], v[132:135], v[190:193], v[80:83]
	v_mfma_f32_16x16x32_bf16 v[76:79], v[140:143], v[190:193], v[76:79]
	v_mfma_f32_16x16x32_bf16 v[128:131], v[136:139], v[152:155], v[128:131]
	v_mfma_f32_16x16x32_bf16 v[124:127], v[144:147], v[152:155], v[124:127]
	v_mfma_f32_16x16x32_bf16 v[112:115], v[136:139], v[160:163], v[112:115]
	v_mfma_f32_16x16x32_bf16 v[108:111], v[144:147], v[160:163], v[108:111]
	v_mfma_f32_16x16x32_bf16 v[96:99], v[136:139], v[186:189], v[96:99]
	v_mfma_f32_16x16x32_bf16 v[92:95], v[144:147], v[186:189], v[92:95]
	v_mfma_f32_16x16x32_bf16 v[80:83], v[136:139], v[202:205], v[80:83]
	v_mfma_f32_16x16x32_bf16 v[76:79], v[144:147], v[202:205], v[76:79]
	s_barrier
	s_add_i32 s47, 0, 0x14000
	s_add_i32 s76, s78, s6
	v_add_u32_e32 v3, s47, v195
	v_lshl_add_u64 v[182:183], s[92:93], 0, v[170:171]
	s_mov_b32 m0, s76
	ds_read_b128 v[206:209], v3
	ds_read_b128 v[222:225], v3 offset:1024
	ds_read_b128 v[226:229], v3 offset:2048
	ds_read_b128 v[230:233], v3 offset:3072
	global_load_lds_dwordx4 v[182:183], off
	v_lshl_add_u64 v[234:235], s[92:93], 0, v[174:175]
	s_add_i32 m0, s76, 0x2000
	s_nop 0
	global_load_lds_dwordx4 v[234:235], off
	s_waitcnt lgkmcnt(0)
	s_barrier
	v_mfma_f32_16x16x32_bf16 v[120:123], v[206:209], v[148:151], v[120:123]
	v_mfma_f32_16x16x32_bf16 v[116:119], v[226:229], v[148:151], v[116:119]
	v_mfma_f32_16x16x32_bf16 v[104:107], v[206:209], v[156:159], v[104:107]
	v_mfma_f32_16x16x32_bf16 v[100:103], v[226:229], v[156:159], v[100:103]
	v_mfma_f32_16x16x32_bf16 v[88:91], v[206:209], v[164:167], v[88:91]
	v_mfma_f32_16x16x32_bf16 v[84:87], v[226:229], v[164:167], v[84:87]
	v_mfma_f32_16x16x32_bf16 v[72:75], v[206:209], v[190:193], v[72:75]
	v_mfma_f32_16x16x32_bf16 v[68:71], v[226:229], v[190:193], v[68:71]
	v_mfma_f32_16x16x32_bf16 v[120:123], v[222:225], v[152:155], v[120:123]
	v_mfma_f32_16x16x32_bf16 v[116:119], v[230:233], v[152:155], v[116:119]
	v_mfma_f32_16x16x32_bf16 v[104:107], v[222:225], v[160:163], v[104:107]
	v_mfma_f32_16x16x32_bf16 v[100:103], v[230:233], v[160:163], v[100:103]
	v_mfma_f32_16x16x32_bf16 v[88:91], v[222:225], v[186:189], v[88:91]
	v_mfma_f32_16x16x32_bf16 v[84:87], v[230:233], v[186:189], v[84:87]
	v_mfma_f32_16x16x32_bf16 v[72:75], v[222:225], v[202:205], v[72:75]
	v_mfma_f32_16x16x32_bf16 v[68:71], v[230:233], v[202:205], v[68:71]
	s_mov_b32 m0, s11
	v_lshl_add_u64 v[236:237], s[74:75], 0, v[168:169]
	s_barrier
	ds_read_b128 v[148:151], v200 offset:16384
	ds_read_b128 v[152:155], v200 offset:17408
	ds_read_b128 v[156:159], v200 offset:18432
	ds_read_b128 v[160:163], v200 offset:19456
	ds_read_b128 v[164:167], v200 offset:20480
	ds_read_b128 v[186:189], v200 offset:21504
	ds_read_b128 v[190:193], v200 offset:22528
	ds_read_b128 v[202:205], v200 offset:23552
	global_load_lds_dwordx4 v[236:237], off
	v_lshl_add_u64 v[238:239], s[74:75], 0, v[172:173]
	s_mov_b32 m0, s70
	s_nop 0
	global_load_lds_dwordx4 v[238:239], off
	s_waitcnt lgkmcnt(0)
	s_barrier
	v_mfma_f32_16x16x32_bf16 v[64:67], v[132:135], v[148:151], v[64:67]
	v_mfma_f32_16x16x32_bf16 v[60:63], v[140:143], v[148:151], v[60:63]
	v_mfma_f32_16x16x32_bf16 v[48:51], v[132:135], v[156:159], v[48:51]
	v_mfma_f32_16x16x32_bf16 v[44:47], v[140:143], v[156:159], v[44:47]
	v_mfma_f32_16x16x32_bf16 v[32:35], v[132:135], v[164:167], v[32:35]
	v_mfma_f32_16x16x32_bf16 v[28:31], v[140:143], v[164:167], v[28:31]
	v_mfma_f32_16x16x32_bf16 v[16:19], v[132:135], v[190:193], v[16:19]
	v_mfma_f32_16x16x32_bf16 v[12:15], v[140:143], v[190:193], v[12:15]
	v_mfma_f32_16x16x32_bf16 v[64:67], v[136:139], v[152:155], v[64:67]
	v_mfma_f32_16x16x32_bf16 v[60:63], v[144:147], v[152:155], v[60:63]
	v_mfma_f32_16x16x32_bf16 v[48:51], v[136:139], v[160:163], v[48:51]
	v_mfma_f32_16x16x32_bf16 v[44:47], v[144:147], v[160:163], v[44:47]
	v_mfma_f32_16x16x32_bf16 v[32:35], v[136:139], v[186:189], v[32:35]
	v_mfma_f32_16x16x32_bf16 v[28:31], v[144:147], v[186:189], v[28:31]
	v_mfma_f32_16x16x32_bf16 v[16:19], v[136:139], v[202:205], v[16:19]
	v_mfma_f32_16x16x32_bf16 v[12:15], v[144:147], v[202:205], v[12:15]
	s_barrier
; #define PG8_STAGE(bufoff, gbase, voff) do { _Pragma("unroll") for (int _i = 0; _i < 2; ++_i) \
;         __builtin_amdgcn_global_load_lds((const unsigned*)((const char*)(gbase) + (voff)[_i]), (LAS unsigned*)(lds + (bufoff) + ldsw + _i * 8192), 16, 0, 0); } while (0)
; #define PG8_LDA(dst, b, h) do { _Pragma("unroll") for (int m = 0; m < 4; ++m) _Pragma("unroll") for (int k = 0; k < 2; ++k) dst[m][k] = *(const LAS bf16x8*)(lds + PG8_SA(b, h) + aoff + m * 2048 + k * 1024); } while (0)
; #define PG8_LDB(dst, b, h) do { _Pragma("unroll") for (int n = 0; n < 2; ++n) _Pragma("unroll") for (int k = 0; k < 2; ++k) dst[n][k] = *(const LAS bf16x8*)(lds + PG8_SB(b, h) + boff + n * 2048 + k * 1024); } while (0)
; #define PG8_MMA(ai, bj, At, Bt) do { __builtin_amdgcn_s_setprio(1); _Pragma("unroll") for (int m = 0; m < 4; ++m) _Pragma("unroll") for (int n = 0; n < 2; ++n) _Pragma("unroll") for (int k = 0; k < 2; ++k) \
;         acc[ai][bj][m][n] = __builtin_amdgcn_mfma_f32_16x16x32_bf16(Bt[n][k], At[m][k], acc[ai][bj][m][n], 0, 0, 0); __builtin_amdgcn_s_setprio(0); } while (0)
; #define PG8_WAIT_V(n) asm volatile("s_waitcnt vmcnt(" #n ")" ::: "memory")
; #define PG8_WAIT_L(n) asm volatile("s_waitcnt lgkmcnt(" #n ")" ::: "memory")
; #define PG8_BAR __builtin_amdgcn_s_barrier()
; #define PG8_SCHED __builtin_amdgcn_sched_barrier(0)
; template <class Epi>
; __device__ __forceinline__ void gemm_phase(LAS unsigned char* lds, const Gemm g, const StaticOrder& S, const Epi& E) {
;     ...
;             PG8_STAGE(PG8_SB(0, 1), b2 + hstep, voffB);
;             PG8_WAIT_V(6); PG8_BAR; PG8_MMA(1, 1, At, B1); PG8_BAR;
;             PG8_LDB(B0, 1, 0); PG8_SCHED; PG8_LDA(At, 1, 0); PG8_STAGE(PG8_SA(0, 1), a2 + hstep, voffA);
;             PG8_WAIT_L(8); PG8_BAR; PG8_WAIT_L(0); PG8_MMA(0, 0, At, B0); PG8_BAR; PG8_SCHED;
;             PG8_LDB(B1, 1, 1); PG8_STAGE(PG8_SB(1, 0), b3, voffB);
;             PG8_BAR; PG8_WAIT_L(0); PG8_MMA(0, 1, At, B1); PG8_BAR;
;             PG8_LDA(At, 1, 1); PG8_STAGE(PG8_SA(1, 0), a3, voffA);
	s_add_u32 s76, s92, s13
	s_addc_u32 s77, s93, 0
	s_add_i32 s47, s47, s6
	v_lshl_add_u64 v[240:241], s[76:77], 0, v[170:171]
	s_mov_b32 m0, s47
	v_lshl_add_u64 v[242:243], s[76:77], 0, v[174:175]
	global_load_lds_dwordx4 v[240:241], off
	s_add_i32 m0, s47, 0x2000
	s_nop 0
	global_load_lds_dwordx4 v[242:243], off
	s_waitcnt vmcnt(6)
	s_barrier
	v_mfma_f32_16x16x32_bf16 v[56:59], v[206:209], v[148:151], v[56:59]
	v_mfma_f32_16x16x32_bf16 v[52:55], v[226:229], v[148:151], v[52:55]
	v_mfma_f32_16x16x32_bf16 v[40:43], v[206:209], v[156:159], v[40:43]
	v_mfma_f32_16x16x32_bf16 v[36:39], v[226:229], v[156:159], v[36:39]
	v_mfma_f32_16x16x32_bf16 v[24:27], v[206:209], v[164:167], v[24:27]
	v_mfma_f32_16x16x32_bf16 v[20:23], v[226:229], v[164:167], v[20:23]
	v_mfma_f32_16x16x32_bf16 v[8:11], v[206:209], v[190:193], v[8:11]
	v_mfma_f32_16x16x32_bf16 v[4:7], v[226:229], v[190:193], v[4:7]
	v_mfma_f32_16x16x32_bf16 v[56:59], v[222:225], v[152:155], v[56:59]
	v_mfma_f32_16x16x32_bf16 v[52:55], v[230:233], v[152:155], v[52:55]
	v_mfma_f32_16x16x32_bf16 v[40:43], v[222:225], v[160:163], v[40:43]
	v_mfma_f32_16x16x32_bf16 v[36:39], v[230:233], v[160:163], v[36:39]
	v_mfma_f32_16x16x32_bf16 v[24:27], v[222:225], v[186:189], v[24:27]
	v_mfma_f32_16x16x32_bf16 v[20:23], v[230:233], v[186:189], v[20:23]
	v_mfma_f32_16x16x32_bf16 v[8:11], v[222:225], v[202:205], v[8:11]
	v_mfma_f32_16x16x32_bf16 v[4:7], v[230:233], v[202:205], v[4:7]
	s_add_i32 s47, 0, 0x18000
	v_add_u32_e32 v3, s47, v195
	s_barrier
	ds_read_b128 v[132:135], v3
	ds_read_b128 v[136:139], v3 offset:1024
	ds_read_b128 v[140:143], v3 offset:2048
	ds_read_b128 v[144:147], v3 offset:3072
	s_add_u32 s74, s74, s13
	s_addc_u32 s75, s75, 0
	s_mov_b32 m0, s71
	v_lshl_add_u64 v[206:207], s[74:75], 0, v[168:169]
	ds_read_b128 v[148:151], v200 offset:32768
	ds_read_b128 v[152:155], v200 offset:33792
	ds_read_b128 v[156:159], v200 offset:34816
	ds_read_b128 v[160:163], v200 offset:35840
	ds_read_b128 v[164:167], v200 offset:36864
	ds_read_b128 v[186:189], v200 offset:37888
	ds_read_b128 v[190:193], v200 offset:38912
	ds_read_b128 v[202:205], v200 offset:39936
	global_load_lds_dwordx4 v[206:207], off
	v_lshl_add_u64 v[206:207], s[74:75], 0, v[172:173]
	s_mov_b32 m0, s19
	s_nop 0
	global_load_lds_dwordx4 v[206:207], off
	s_waitcnt lgkmcnt(0)
	s_barrier
	v_mfma_f32_16x16x32_bf16 v[128:131], v[132:135], v[148:151], v[128:131]
	v_mfma_f32_16x16x32_bf16 v[124:127], v[140:143], v[148:151], v[124:127]
	v_mfma_f32_16x16x32_bf16 v[112:115], v[132:135], v[156:159], v[112:115]
	v_mfma_f32_16x16x32_bf16 v[108:111], v[140:143], v[156:159], v[108:111]
	v_mfma_f32_16x16x32_bf16 v[96:99], v[132:135], v[164:167], v[96:99]
	v_mfma_f32_16x16x32_bf16 v[92:95], v[140:143], v[164:167], v[92:95]
	v_mfma_f32_16x16x32_bf16 v[80:83], v[132:135], v[190:193], v[80:83]
	v_mfma_f32_16x16x32_bf16 v[76:79], v[140:143], v[190:193], v[76:79]
	v_mfma_f32_16x16x32_bf16 v[128:131], v[136:139], v[152:155], v[128:131]
	v_mfma_f32_16x16x32_bf16 v[124:127], v[144:147], v[152:155], v[124:127]
	v_mfma_f32_16x16x32_bf16 v[112:115], v[136:139], v[160:163], v[112:115]
	v_mfma_f32_16x16x32_bf16 v[108:111], v[144:147], v[160:163], v[108:111]
	v_mfma_f32_16x16x32_bf16 v[96:99], v[136:139], v[186:189], v[96:99]
	v_mfma_f32_16x16x32_bf16 v[92:95], v[144:147], v[186:189], v[92:95]
	v_mfma_f32_16x16x32_bf16 v[80:83], v[136:139], v[202:205], v[80:83]
	v_mfma_f32_16x16x32_bf16 v[76:79], v[144:147], v[202:205], v[76:79]
	s_barrier
	s_add_i32 s74, 0, 0x1c000
	s_add_i32 s47, s47, s6
	v_add_u32_e32 v3, s74, v195
	v_lshl_add_u64 v[182:183], v[182:183], 0, s[20:21]
	s_mov_b32 m0, s47
	ds_read_b128 v[206:209], v3
	ds_read_b128 v[222:225], v3 offset:1024
	ds_read_b128 v[226:229], v3 offset:2048
	ds_read_b128 v[230:233], v3 offset:3072
	global_load_lds_dwordx4 v[182:183], off
	v_lshl_add_u64 v[182:183], v[234:235], 0, s[20:21]
	s_add_i32 m0, s47, 0x2000
	s_nop 0
	global_load_lds_dwordx4 v[182:183], off
	s_waitcnt lgkmcnt(0)
	s_barrier
; #define PG8_STAGE(bufoff, gbase, voff) do { _Pragma("unroll") for (int _i = 0; _i < 2; ++_i) \
;         __builtin_amdgcn_global_load_lds((const unsigned*)((const char*)(gbase) + (voff)[_i]), (LAS unsigned*)(lds + (bufoff) + ldsw + _i * 8192), 16, 0, 0); } while (0)
; #define PG8_LDA(dst, b, h) do { _Pragma("unroll") for (int m = 0; m < 4; ++m) _Pragma("unroll") for (int k = 0; k < 2; ++k) dst[m][k] = *(const LAS bf16x8*)(lds + PG8_SA(b, h) + aoff + m * 2048 + k * 1024); } while (0)
; #define PG8_LDB(dst, b, h) do { _Pragma("unroll") for (int n = 0; n < 2; ++n) _Pragma("unroll") for (int k = 0; k < 2; ++k) dst[n][k] = *(const LAS bf16x8*)(lds + PG8_SB(b, h) + boff + n * 2048 + k * 1024); } while (0)
; #define PG8_MMA(ai, bj, At, Bt) do { __builtin_amdgcn_s_setprio(1); _Pragma("unroll") for (int m = 0; m < 4; ++m) _Pragma("unroll") for (int n = 0; n < 2; ++n) _Pragma("unroll") for (int k = 0; k < 2; ++k) \
;         acc[ai][bj][m][n] = __builtin_amdgcn_mfma_f32_16x16x32_bf16(Bt[n][k], At[m][k], acc[ai][bj][m][n], 0, 0, 0); __builtin_amdgcn_s_setprio(0); } while (0)
; #define PG8_WAIT_V(n) asm volatile("s_waitcnt vmcnt(" #n ")" ::: "memory")
; #define PG8_WAIT_L(n) asm volatile("s_waitcnt lgkmcnt(" #n ")" ::: "memory")
; #define PG8_BAR __builtin_amdgcn_s_barrier()
; #define PG8_SCHED __builtin_amdgcn_sched_barrier(0)
; template <class Epi>
; __device__ __forceinline__ void gemm_phase(LAS unsigned char* lds, const Gemm g, const StaticOrder& S, const Epi& E) {
;     ...
;             PG8_LDB(B1, 1, 1); PG8_STAGE(PG8_SB(1, 0), b3, voffB);
;             PG8_BAR; PG8_WAIT_L(0); PG8_MMA(0, 1, At, B1); PG8_BAR;
;             PG8_LDA(At, 1, 1); PG8_STAGE(PG8_SA(1, 0), a3, voffA);
;             PG8_BAR; PG8_WAIT_L(0); PG8_MMA(1, 0, At, B0); PG8_BAR; PG8_SCHED;
;             PG8_STAGE(PG8_SB(1, 1), b3 + hstep, voffB);
;             PG8_WAIT_V(6); PG8_BAR; PG8_MMA(1, 1, At, B1); PG8_BAR;
	v_mfma_f32_16x16x32_bf16 v[120:123], v[206:209], v[148:151], v[120:123]
	v_mfma_f32_16x16x32_bf16 v[116:119], v[226:229], v[148:151], v[116:119]
	v_mfma_f32_16x16x32_bf16 v[104:107], v[206:209], v[156:159], v[104:107]
	v_mfma_f32_16x16x32_bf16 v[100:103], v[226:229], v[156:159], v[100:103]
	v_mfma_f32_16x16x32_bf16 v[88:91], v[206:209], v[164:167], v[88:91]
	v_mfma_f32_16x16x32_bf16 v[84:87], v[226:229], v[164:167], v[84:87]
	v_mfma_f32_16x16x32_bf16 v[72:75], v[206:209], v[190:193], v[72:75]
	v_mfma_f32_16x16x32_bf16 v[68:71], v[226:229], v[190:193], v[68:71]
	v_mfma_f32_16x16x32_bf16 v[120:123], v[222:225], v[152:155], v[120:123]
	v_mfma_f32_16x16x32_bf16 v[116:119], v[230:233], v[152:155], v[116:119]
	v_mfma_f32_16x16x32_bf16 v[104:107], v[222:225], v[160:163], v[104:107]
	v_mfma_f32_16x16x32_bf16 v[100:103], v[230:233], v[160:163], v[100:103]
	v_mfma_f32_16x16x32_bf16 v[88:91], v[222:225], v[186:189], v[88:91]
	v_mfma_f32_16x16x32_bf16 v[84:87], v[230:233], v[186:189], v[84:87]
	v_mfma_f32_16x16x32_bf16 v[72:75], v[222:225], v[202:205], v[72:75]
	v_mfma_f32_16x16x32_bf16 v[68:71], v[230:233], v[202:205], v[68:71]
	s_mov_b32 m0, s33
	v_lshl_add_u64 v[182:183], v[236:237], 0, s[20:21]
	s_barrier
	ds_read_b128 v[148:151], v200 offset:49152
	ds_read_b128 v[152:155], v200 offset:50176
	ds_read_b128 v[156:159], v200 offset:51200
	ds_read_b128 v[160:163], v200 offset:52224
	ds_read_b128 v[164:167], v200 offset:53248
	ds_read_b128 v[186:189], v200 offset:54272
	ds_read_b128 v[190:193], v200 offset:55296
	ds_read_b128 v[202:205], v200 offset:56320
	global_load_lds_dwordx4 v[182:183], off
	v_lshl_add_u64 v[182:183], v[238:239], 0, s[20:21]
	s_mov_b32 m0, s66
	s_nop 0
	global_load_lds_dwordx4 v[182:183], off
	s_waitcnt lgkmcnt(0)
	s_barrier
	v_mfma_f32_16x16x32_bf16 v[64:67], v[132:135], v[148:151], v[64:67]
	v_mfma_f32_16x16x32_bf16 v[60:63], v[140:143], v[148:151], v[60:63]
	v_mfma_f32_16x16x32_bf16 v[48:51], v[132:135], v[156:159], v[48:51]
	v_mfma_f32_16x16x32_bf16 v[44:47], v[140:143], v[156:159], v[44:47]
	v_mfma_f32_16x16x32_bf16 v[32:35], v[132:135], v[164:167], v[32:35]
	v_mfma_f32_16x16x32_bf16 v[28:31], v[140:143], v[164:167], v[28:31]
	v_mfma_f32_16x16x32_bf16 v[16:19], v[132:135], v[190:193], v[16:19]
	v_mfma_f32_16x16x32_bf16 v[12:15], v[140:143], v[190:193], v[12:15]
	v_mfma_f32_16x16x32_bf16 v[64:67], v[136:139], v[152:155], v[64:67]
	v_mfma_f32_16x16x32_bf16 v[60:63], v[144:147], v[152:155], v[60:63]
	v_mfma_f32_16x16x32_bf16 v[48:51], v[136:139], v[160:163], v[48:51]
	v_mfma_f32_16x16x32_bf16 v[44:47], v[144:147], v[160:163], v[44:47]
	v_mfma_f32_16x16x32_bf16 v[32:35], v[136:139], v[186:189], v[32:35]
	v_mfma_f32_16x16x32_bf16 v[28:31], v[144:147], v[186:189], v[28:31]
	v_mfma_f32_16x16x32_bf16 v[16:19], v[136:139], v[202:205], v[16:19]
	v_mfma_f32_16x16x32_bf16 v[12:15], v[144:147], v[202:205], v[12:15]
	s_barrier
	s_add_i32 s47, s74, s6
	v_lshl_add_u64 v[132:133], v[240:241], 0, s[20:21]
	s_mov_b32 m0, s47
	s_nop 0
	global_load_lds_dwordx4 v[132:133], off
	v_lshl_add_u64 v[132:133], v[242:243], 0, s[20:21]
	s_add_i32 m0, s47, 0x2000
	s_nop 0
	global_load_lds_dwordx4 v[132:133], off
	s_waitcnt vmcnt(6)
	s_barrier
	v_mfma_f32_16x16x32_bf16 v[56:59], v[206:209], v[148:151], v[56:59]
	v_mfma_f32_16x16x32_bf16 v[52:55], v[226:229], v[148:151], v[52:55]
	v_mfma_f32_16x16x32_bf16 v[40:43], v[206:209], v[156:159], v[40:43]
	v_mfma_f32_16x16x32_bf16 v[36:39], v[226:229], v[156:159], v[36:39]
	v_mfma_f32_16x16x32_bf16 v[24:27], v[206:209], v[164:167], v[24:27]
	v_mfma_f32_16x16x32_bf16 v[20:23], v[226:229], v[164:167], v[20:23]
	v_mfma_f32_16x16x32_bf16 v[8:11], v[206:209], v[190:193], v[8:11]
	v_mfma_f32_16x16x32_bf16 v[4:7], v[226:229], v[190:193], v[4:7]
	v_mfma_f32_16x16x32_bf16 v[56:59], v[222:225], v[152:155], v[56:59]
	v_mfma_f32_16x16x32_bf16 v[52:55], v[230:233], v[152:155], v[52:55]
	v_mfma_f32_16x16x32_bf16 v[40:43], v[222:225], v[160:163], v[40:43]
	v_mfma_f32_16x16x32_bf16 v[36:39], v[230:233], v[160:163], v[36:39]
	v_mfma_f32_16x16x32_bf16 v[24:27], v[222:225], v[186:189], v[24:27]
	v_mfma_f32_16x16x32_bf16 v[20:23], v[230:233], v[186:189], v[20:23]
	v_mfma_f32_16x16x32_bf16 v[8:11], v[222:225], v[202:205], v[8:11]
	v_mfma_f32_16x16x32_bf16 v[4:7], v[230:233], v[202:205], v[4:7]
	s_add_u32 s3, s3, 0x100
	s_addc_u32 vcc_lo, vcc_lo, 0
	s_add_u32 vcc_hi, vcc_hi, 0x100
	s_addc_u32 s46, s46, 0
	s_cmp_lt_i32 s2, s57
	s_barrier
	s_cbranch_scc1 .LBB0_206
	s_movk_i32 s92, 0x90
	s_mov_b32 s93, 0x3f317217

; #define PG8_WAIT_V(n) asm volatile("s_waitcnt vmcnt(" #n ")" ::: "memory")
; #define PG8_BAR __builtin_amdgcn_s_barrier()
; template <class Epi>
; __device__ __forceinline__ void gemm_phase(LAS unsigned char* lds, const Gemm g, const StaticOrder& S, const Epi& E) {
;     ...
;     PG8_WAIT_V(0);
;     if (wr == 0) PG8_BAR;
;     PG8_BAR;
.LBB0_248:
	s_setprio 0
	s_waitcnt vmcnt(0)
	v_readlane_b32 s1, v245, 51
	s_cmpk_gt_u32 s1, 0xff
	s_cbranch_scc1 .LBB0_250
	s_barrier
